# P1 full-line k-loop + s_setprio 1 around MFMA bursts + P1 tile band height 16 (16Mx4N tile groups per XCD)
# baseline (speedup 1.0000x reference)
; DI void phase1(const XcdMap xm, const int wv, const Params& p0, int l, char* s0, char* s1, char* s2) {
;     ...
;   for (int t = xm.rank; t < total; t += xm.nlb) {
;     int mtile, ntile;
;     xcd_tile(t, m_start, m_cnt, 22, mtile, ntile);
;     const int m0 = mtile * 128, n0 = ntile * 256;
;     if (ntile == 21) {
.LBB0_911:
	s_mul_hi_i32 s2, s63, 0x2e8ba2e9
	s_lshr_b32 s3, s2, 31
	s_ashr_i32 s2, s2, 6
	s_add_i32 s86, s2, s3
	s_lshl_b32 s2, s86, 4
	s_sub_i32 s3, s58, s2
	s_min_i32 s85, s3, 16
	s_abs_i32 s3, s85
	v_cvt_f32_u32_e32 v0, s3
	s_mul_i32 s8, s86, 0xfffffea0
	s_add_i32 s8, s8, s63
	s_xor_b32 s20, s8, s85
	v_rcp_iflag_f32_e32 v0, v0
	s_ashr_i32 s78, s20, 31
	s_sub_i32 s20, 0, s3
	s_abs_i32 s9, s8
	v_mul_f32_e32 v0, 0x4f7ffffe, v0
	v_cvt_u32_f32_e32 v0, v0
	s_mulk_i32 s86, 0x150
	v_readfirstlane_b32 s21, v0
	s_mul_i32 s20, s20, s21
	s_mul_hi_u32 s20, s21, s20
	s_add_i32 s21, s21, s20
	s_mul_hi_u32 s20, s9, s21
	s_mul_i32 s21, s20, s3
	s_sub_i32 s9, s9, s21
	s_add_i32 s28, s20, 1
	s_sub_i32 s21, s9, s3
	s_cmp_ge_u32 s9, s3
	s_cselect_b32 s20, s28, s20
	s_cselect_b32 s9, s21, s9
	s_add_i32 s21, s20, 1
	s_cmp_ge_u32 s9, s3
	s_cselect_b32 s3, s21, s20
	s_xor_b32 s84, s3, s78
	s_sub_i32 s28, s84, s78
	s_add_i32 s2, s61, s2
	s_mul_i32 s85, s85, s28
	s_add_i32 s2, s2, s8
	s_sub_i32 s2, s2, s85
	s_lshl_b32 s42, s28, 8
	s_lshl_b32 s2, s2, 7
	s_sub_i32 s87, 0x151f, s42
	s_cmp_lg_u32 s28, 21
	s_mov_b64 s[8:9], -1
	s_cbranch_scc1 .LBB0_913
	s_and_b64 vcc, exec, s[8:9]
	s_cbranch_vccz .LBB0_910
	s_branch .LBB0_944

; template <int BM, int BN, int WR, int WC, int NSWAP, bool PERM = false>
; DI void gemm_ring(const int tid_, const u16* __restrict__ Ab, int lda, const u16* __restrict__ Bt, int ldb, int brow_max, int nk,
;                   char* s0, char* s1, char* s2, f32x4 (&acc)[BM / WR / 16][BN / WC / 16]) {
;     ...
;   auto step = [&](int kt, char* cur, char* nxt) {
;     if (kt + 1 < nk) WAIT_V(LPW); else WAIT_V(0);
;     raw_barrier();
;     if (kt + 2 < nk) issue(nxt, kt + 2);
;     const unsigned aA = (unsigned)(size_t)cur + (unsigned)((wr * WM) * 64 + fo);
;     const unsigned aB = (unsigned)(size_t)cur + (unsigned)(SA + (wc * WN) * 64 + fo);
;     bf16x8 xf[MT], wf[NT];
;     xf[0] = ldsr<0>(aA);
;     if constexpr (MT > 1) xf[1] = ldsr<1024>(aA);
;     if constexpr (MT > 2) xf[2] = ldsr<2048>(aA);
;     if constexpr (MT > 3) xf[3] = ldsr<3072>(aA);
;     if constexpr (MT > 4) xf[4] = ldsr<4096>(aA);
;     if constexpr (MT > 5) xf[5] = ldsr<5120>(aA);
;     wf[0] = ldsr<0>(aB);
;     if constexpr (NT > 1) wf[1] = ldsr<1024>(aB);
;     if constexpr (NT > 2) wf[2] = ldsr<2048>(aB);
;     if constexpr (NT > 3) wf[3] = ldsr<3072>(aB);
;     if constexpr (NT > 4) wf[4] = ldsr<4096>(aB);
;     if constexpr (NT > 5) wf[5] = ldsr<5120>(aB);
;     if constexpr (NT > 6) wf[6] = ldsr<6144>(aB);
;     if constexpr (NT > 7) wf[7] = ldsr<7168>(aB);
;     constexpr int NH = NT / 2;
;     asm volatile("s_waitcnt lgkmcnt(%0)" ::"n"(NT - NH) : "memory");
; #pragma unroll
;     for (int mt = 0; mt < MT; ++mt) asm volatile("" : "+v"(xf[mt]));
; #pragma unroll
;     for (int nt = 0; nt < NH; ++nt) asm volatile("" : "+v"(wf[nt]));
; #pragma unroll
;     for (int nt = 0; nt < NH; ++nt) {
; #pragma unroll
;       for (int mt = 0; mt < MT; ++mt) {
;         if (nt < NSWAP) acc[mt][nt] = __builtin_amdgcn_mfma_f32_16x16x32_bf16(wf[nt], xf[mt], acc[mt][nt], 0, 0, 0);
;         else acc[mt][nt] = __builtin_amdgcn_mfma_f32_16x16x32_bf16(xf[mt], wf[nt], acc[mt][nt], 0, 0, 0);
;       }
;     }
;     asm volatile("s_waitcnt lgkmcnt(0)" ::: "memory");
; #pragma unroll
;     for (int nt = NH; nt < NT; ++nt) asm volatile("" : "+v"(wf[nt]));
; #pragma unroll
;     for (int nt = NH; nt < NT; ++nt) {
; #pragma unroll
;       for (int mt = 0; mt < MT; ++mt) {
;         if (nt < NSWAP) acc[mt][nt] = __builtin_amdgcn_mfma_f32_16x16x32_bf16(wf[nt], xf[mt], acc[mt][nt], 0, 0, 0);
.Lp1_loop:
	s_waitcnt vmcnt(4)
	s_barrier
	v_add_u32_e32 v165, s70, v202
	v_add_u32_e32 v0, s71, v204
	ds_read_b128 v[206:209], v165 offset:0
	ds_read_b128 v[210:213], v165 offset:2048
	ds_read_b128 v[214:217], v165 offset:4096
	ds_read_b128 v[218:221], v165 offset:6144
	ds_read_b128 v[238:241], v0 offset:0
	ds_read_b128 v[242:245], v0 offset:2048
	ds_read_b128 v[246:249], v0 offset:4096
	ds_read_b128 v[172:175], v0 offset:6144
	v_add_u32_e32 v165, s70, v203
	v_add_u32_e32 v0, s71, v164
	ds_read_b128 v[222:225], v165 offset:0
	ds_read_b128 v[226:229], v165 offset:2048
	ds_read_b128 v[230:233], v165 offset:4096
	ds_read_b128 v[234:237], v165 offset:6144
	s_waitcnt lgkmcnt(4)
	s_setprio 1
	v_mfma_f32_16x16x32_bf16 v[128:131], v[238:241], v[206:209], v[128:131]
	v_mfma_f32_16x16x32_bf16 v[96:99], v[238:241], v[210:213], v[96:99]
	v_mfma_f32_16x16x32_bf16 v[64:67], v[238:241], v[214:217], v[64:67]
	v_mfma_f32_16x16x32_bf16 v[32:35], v[238:241], v[218:221], v[32:35]
	v_mfma_f32_16x16x32_bf16 v[124:127], v[242:245], v[206:209], v[124:127]
	v_mfma_f32_16x16x32_bf16 v[92:95], v[242:245], v[210:213], v[92:95]
	v_mfma_f32_16x16x32_bf16 v[60:63], v[242:245], v[214:217], v[60:63]
	v_mfma_f32_16x16x32_bf16 v[28:31], v[242:245], v[218:221], v[28:31]
	ds_read_b128 v[156:159], v0 offset:0
	ds_read_b128 v[160:163], v0 offset:2048
	ds_read_b128 v[194:197], v0 offset:4096
	ds_read_b128 v[198:201], v0 offset:6144
	v_mfma_f32_16x16x32_bf16 v[120:123], v[246:249], v[206:209], v[120:123]
	v_mfma_f32_16x16x32_bf16 v[88:91], v[246:249], v[210:213], v[88:91]
	s_mov_b32 m0, s73
	s_nop 0
	global_load_lds_dwordx4 v2, s[76:77]
	v_mfma_f32_16x16x32_bf16 v[56:59], v[246:249], v[214:217], v[56:59]
	v_mfma_f32_16x16x32_bf16 v[24:27], v[246:249], v[218:221], v[24:27]
	s_add_u32 m0, s73, 0x400
	s_add_u32 s8, s76, 0x4000
	s_addc_u32 s9, s77, 0
	global_load_lds_dwordx4 v2, s[8:9]
	v_mfma_f32_16x16x32_bf16 v[116:119], v[172:175], v[206:209], v[116:119]
	v_mfma_f32_16x16x32_bf16 v[84:87], v[172:175], v[210:213], v[84:87]
	s_add_u32 m0, s73, 0x800
	s_add_u32 s8, s76, 0x8000
	s_addc_u32 s9, s77, 0
	global_load_lds_dwordx4 v2, s[8:9]
	v_mfma_f32_16x16x32_bf16 v[52:55], v[172:175], v[214:217], v[52:55]
	v_mfma_f32_16x16x32_bf16 v[20:23], v[172:175], v[218:221], v[20:23]
	s_add_u32 m0, s73, 0xc00
	s_add_u32 s8, s76, 0xc000
	s_addc_u32 s9, s77, 0
	global_load_lds_dwordx4 v2, s[8:9]
	s_waitcnt lgkmcnt(0)
	v_mfma_f32_16x16x32_bf16 v[128:131], v[156:159], v[222:225], v[128:131]
	v_mfma_f32_16x16x32_bf16 v[96:99], v[156:159], v[226:229], v[96:99]
	s_mov_b32 m0, s74
	s_nop 0
	global_load_lds_dwordx4 v3, s[52:53]
	v_mfma_f32_16x16x32_bf16 v[64:67], v[156:159], v[230:233], v[64:67]
	v_mfma_f32_16x16x32_bf16 v[32:35], v[156:159], v[234:237], v[32:35]
	s_add_u32 m0, s74, 0x400
	s_add_u32 s8, s52, 0x20000
	s_addc_u32 s9, s53, 0
	global_load_lds_dwordx4 v3, s[8:9]
	v_mfma_f32_16x16x32_bf16 v[124:127], v[160:163], v[222:225], v[124:127]
	v_mfma_f32_16x16x32_bf16 v[92:95], v[160:163], v[226:229], v[92:95]
	s_add_u32 m0, s74, 0x800
	s_add_u32 s8, s52, 0x2000
	s_addc_u32 s9, s53, 0
	global_load_lds_dwordx4 v3, s[8:9]
	v_mfma_f32_16x16x32_bf16 v[60:63], v[160:163], v[230:233], v[60:63]
	v_mfma_f32_16x16x32_bf16 v[28:31], v[160:163], v[234:237], v[28:31]
	s_add_u32 m0, s74, 0xc00
	s_add_u32 s8, s52, 0x22000
	s_addc_u32 s9, s53, 0
	global_load_lds_dwordx4 v3, s[8:9]
	v_mfma_f32_16x16x32_bf16 v[120:123], v[194:197], v[222:225], v[120:123]
	v_mfma_f32_16x16x32_bf16 v[88:91], v[194:197], v[226:229], v[88:91]
	v_mfma_f32_16x16x32_bf16 v[56:59], v[194:197], v[230:233], v[56:59]
	v_mfma_f32_16x16x32_bf16 v[24:27], v[194:197], v[234:237], v[24:27]
	v_mfma_f32_16x16x32_bf16 v[116:119], v[198:201], v[222:225], v[116:119]
	v_mfma_f32_16x16x32_bf16 v[84:87], v[198:201], v[226:229], v[84:87]
	v_mfma_f32_16x16x32_bf16 v[52:55], v[198:201], v[230:233], v[52:55]
	v_mfma_f32_16x16x32_bf16 v[20:23], v[198:201], v[234:237], v[20:23]
	s_setprio 0
	s_waitcnt vmcnt(8)
	s_barrier
	v_add_u32_e32 v165, s72, v204
	v_add_u32_e32 v0, s72, v164
	ds_read_b128 v[238:241], v165 offset:0
	ds_read_b128 v[242:245], v165 offset:2048
	ds_read_b128 v[246:249], v165 offset:4096
	ds_read_b128 v[172:175], v165 offset:6144
	ds_read_b128 v[156:159], v0 offset:0
	ds_read_b128 v[160:163], v0 offset:2048
	ds_read_b128 v[194:197], v0 offset:4096
	ds_read_b128 v[198:201], v0 offset:6144
	s_waitcnt lgkmcnt(4)
	s_setprio 1
	v_mfma_f32_16x16x32_bf16 v[112:115], v[238:241], v[206:209], v[112:115]
	v_mfma_f32_16x16x32_bf16 v[80:83], v[238:241], v[210:213], v[80:83]
	v_mfma_f32_16x16x32_bf16 v[48:51], v[238:241], v[214:217], v[48:51]
	v_mfma_f32_16x16x32_bf16 v[16:19], v[238:241], v[218:221], v[16:19]
	s_mov_b32 m0, s71
	s_add_u32 s8, s52, 0x8000
	s_addc_u32 s9, s53, 0
	global_load_lds_dwordx4 v3, s[8:9]
	v_mfma_f32_16x16x32_bf16 v[108:111], v[242:245], v[206:209], v[108:111]
	v_mfma_f32_16x16x32_bf16 v[76:79], v[242:245], v[210:213], v[76:79]
	v_mfma_f32_16x16x32_bf16 v[44:47], v[242:245], v[214:217], v[44:47]
	v_mfma_f32_16x16x32_bf16 v[12:15], v[242:245], v[218:221], v[12:15]
	s_add_u32 m0, s71, 0x400
	s_add_u32 s8, s52, 0x28000
	s_addc_u32 s9, s53, 0
	global_load_lds_dwordx4 v3, s[8:9]
	v_mfma_f32_16x16x32_bf16 v[104:107], v[246:249], v[206:209], v[104:107]
	v_mfma_f32_16x16x32_bf16 v[72:75], v[246:249], v[210:213], v[72:75]
	v_mfma_f32_16x16x32_bf16 v[40:43], v[246:249], v[214:217], v[40:43]
	v_mfma_f32_16x16x32_bf16 v[8:11], v[246:249], v[218:221], v[8:11]
	s_add_u32 m0, s71, 0x800
	s_add_u32 s8, s52, 0xa000
	s_addc_u32 s9, s53, 0
	global_load_lds_dwordx4 v3, s[8:9]
	v_mfma_f32_16x16x32_bf16 v[100:103], v[172:175], v[206:209], v[100:103]
	v_mfma_f32_16x16x32_bf16 v[68:71], v[172:175], v[210:213], v[68:71]
	v_mfma_f32_16x16x32_bf16 v[36:39], v[172:175], v[214:217], v[36:39]
	v_mfma_f32_16x16x32_bf16 v[4:7], v[172:175], v[218:221], v[4:7]
	s_add_u32 m0, s71, 0xc00
	s_add_u32 s8, s52, 0x2a000
	s_addc_u32 s9, s53, 0
	global_load_lds_dwordx4 v3, s[8:9]
	s_waitcnt lgkmcnt(0)
; template <int BM, int BN, int WR, int WC, int NSWAP, bool PERM = false>
; DI void gemm_ring(const int tid_, const u16* __restrict__ Ab, int lda, const u16* __restrict__ Bt, int ldb, int brow_max, int nk,
;                   char* s0, char* s1, char* s2, f32x4 (&acc)[BM / WR / 16][BN / WC / 16]) {
;     ...
;   auto step = [&](int kt, char* cur, char* nxt) {
;     if (kt + 1 < nk) WAIT_V(LPW); else WAIT_V(0);
;     raw_barrier();
;     if (kt + 2 < nk) issue(nxt, kt + 2);
;     const unsigned aA = (unsigned)(size_t)cur + (unsigned)((wr * WM) * 64 + fo);
;     const unsigned aB = (unsigned)(size_t)cur + (unsigned)(SA + (wc * WN) * 64 + fo);
;     bf16x8 xf[MT], wf[NT];
;     xf[0] = ldsr<0>(aA);
;     if constexpr (MT > 1) xf[1] = ldsr<1024>(aA);
;     if constexpr (MT > 2) xf[2] = ldsr<2048>(aA);
;     if constexpr (MT > 3) xf[3] = ldsr<3072>(aA);
;     if constexpr (MT > 4) xf[4] = ldsr<4096>(aA);
;     if constexpr (MT > 5) xf[5] = ldsr<5120>(aA);
;     wf[0] = ldsr<0>(aB);
;     if constexpr (NT > 1) wf[1] = ldsr<1024>(aB);
;     if constexpr (NT > 2) wf[2] = ldsr<2048>(aB);
;     if constexpr (NT > 3) wf[3] = ldsr<3072>(aB);
;     if constexpr (NT > 4) wf[4] = ldsr<4096>(aB);
;     if constexpr (NT > 5) wf[5] = ldsr<5120>(aB);
;     if constexpr (NT > 6) wf[6] = ldsr<6144>(aB);
;     if constexpr (NT > 7) wf[7] = ldsr<7168>(aB);
;     constexpr int NH = NT / 2;
;     asm volatile("s_waitcnt lgkmcnt(%0)" ::"n"(NT - NH) : "memory");
; #pragma unroll
;     for (int mt = 0; mt < MT; ++mt) asm volatile("" : "+v"(xf[mt]));
; #pragma unroll
;     for (int nt = 0; nt < NH; ++nt) asm volatile("" : "+v"(wf[nt]));
; #pragma unroll
;     for (int nt = 0; nt < NH; ++nt) {
; #pragma unroll
;       for (int mt = 0; mt < MT; ++mt) {
;         if (nt < NSWAP) acc[mt][nt] = __builtin_amdgcn_mfma_f32_16x16x32_bf16(wf[nt], xf[mt], acc[mt][nt], 0, 0, 0);
;         else acc[mt][nt] = __builtin_amdgcn_mfma_f32_16x16x32_bf16(xf[mt], wf[nt], acc[mt][nt], 0, 0, 0);
;       }
;     }
;     asm volatile("s_waitcnt lgkmcnt(0)" ::: "memory");
; #pragma unroll
;     for (int nt = NH; nt < NT; ++nt) asm volatile("" : "+v"(wf[nt]));
; #pragma unroll
;     for (int nt = NH; nt < NT; ++nt) {
; #pragma unroll
;       for (int mt = 0; mt < MT; ++mt) {
;         if (nt < NSWAP) acc[mt][nt] = __builtin_amdgcn_mfma_f32_16x16x32_bf16(wf[nt], xf[mt], acc[mt][nt], 0, 0, 0);
	v_mfma_f32_16x16x32_bf16 v[112:115], v[156:159], v[222:225], v[112:115]
	v_mfma_f32_16x16x32_bf16 v[80:83], v[156:159], v[226:229], v[80:83]
	v_mfma_f32_16x16x32_bf16 v[48:51], v[156:159], v[230:233], v[48:51]
	v_mfma_f32_16x16x32_bf16 v[16:19], v[156:159], v[234:237], v[16:19]
	v_mfma_f32_16x16x32_bf16 v[108:111], v[160:163], v[222:225], v[108:111]
	v_mfma_f32_16x16x32_bf16 v[76:79], v[160:163], v[226:229], v[76:79]
	v_mfma_f32_16x16x32_bf16 v[44:47], v[160:163], v[230:233], v[44:47]
	v_mfma_f32_16x16x32_bf16 v[12:15], v[160:163], v[234:237], v[12:15]
	v_mfma_f32_16x16x32_bf16 v[104:107], v[194:197], v[222:225], v[104:107]
	v_mfma_f32_16x16x32_bf16 v[72:75], v[194:197], v[226:229], v[72:75]
	v_mfma_f32_16x16x32_bf16 v[40:43], v[194:197], v[230:233], v[40:43]
	v_mfma_f32_16x16x32_bf16 v[8:11], v[194:197], v[234:237], v[8:11]
	v_mfma_f32_16x16x32_bf16 v[100:103], v[198:201], v[222:225], v[100:103]
	v_mfma_f32_16x16x32_bf16 v[68:71], v[198:201], v[226:229], v[68:71]
	v_mfma_f32_16x16x32_bf16 v[36:39], v[198:201], v[230:233], v[36:39]
	v_mfma_f32_16x16x32_bf16 v[4:7], v[198:201], v[234:237], v[4:7]
	s_setprio 0
	s_mov_b32 s8, s70
	s_mov_b32 s9, s72
	s_mov_b32 s70, s73
	s_mov_b32 s72, s71
	s_mov_b32 s71, s74
	s_mov_b32 s73, s8
	s_mov_b32 s74, s9
	s_add_u32 s76, s76, 0x80
	s_addc_u32 s77, s77, 0
	s_add_u32 s52, s52, 0x80
	s_addc_u32 s53, s53, 0
	s_add_u32 s3, s3, 1
	s_cmp_lt_u32 s3, 15
	s_cbranch_scc1 .Lp1_loop
	s_waitcnt vmcnt(4)
	s_barrier
	v_add_u32_e32 v165, s70, v202
	v_add_u32_e32 v0, s71, v204
	ds_read_b128 v[206:209], v165 offset:0
	ds_read_b128 v[210:213], v165 offset:2048
	ds_read_b128 v[214:217], v165 offset:4096
	ds_read_b128 v[218:221], v165 offset:6144
	ds_read_b128 v[238:241], v0 offset:0
	ds_read_b128 v[242:245], v0 offset:2048
	ds_read_b128 v[246:249], v0 offset:4096
	ds_read_b128 v[172:175], v0 offset:6144
	v_add_u32_e32 v165, s70, v203
	v_add_u32_e32 v0, s71, v164
	ds_read_b128 v[222:225], v165 offset:0
	ds_read_b128 v[226:229], v165 offset:2048
	ds_read_b128 v[230:233], v165 offset:4096
	ds_read_b128 v[234:237], v165 offset:6144
	s_waitcnt lgkmcnt(4)
	s_setprio 1
	v_mfma_f32_16x16x32_bf16 v[128:131], v[238:241], v[206:209], v[128:131]
	v_mfma_f32_16x16x32_bf16 v[96:99], v[238:241], v[210:213], v[96:99]
	v_mfma_f32_16x16x32_bf16 v[64:67], v[238:241], v[214:217], v[64:67]
	v_mfma_f32_16x16x32_bf16 v[32:35], v[238:241], v[218:221], v[32:35]
	v_mfma_f32_16x16x32_bf16 v[124:127], v[242:245], v[206:209], v[124:127]
	v_mfma_f32_16x16x32_bf16 v[92:95], v[242:245], v[210:213], v[92:95]
	v_mfma_f32_16x16x32_bf16 v[60:63], v[242:245], v[214:217], v[60:63]
	v_mfma_f32_16x16x32_bf16 v[28:31], v[242:245], v[218:221], v[28:31]
	ds_read_b128 v[156:159], v0 offset:0
	ds_read_b128 v[160:163], v0 offset:2048
	ds_read_b128 v[194:197], v0 offset:4096
	ds_read_b128 v[198:201], v0 offset:6144
	v_mfma_f32_16x16x32_bf16 v[120:123], v[246:249], v[206:209], v[120:123]
	v_mfma_f32_16x16x32_bf16 v[88:91], v[246:249], v[210:213], v[88:91]
	v_mfma_f32_16x16x32_bf16 v[56:59], v[246:249], v[214:217], v[56:59]
	v_mfma_f32_16x16x32_bf16 v[24:27], v[246:249], v[218:221], v[24:27]
	v_mfma_f32_16x16x32_bf16 v[116:119], v[172:175], v[206:209], v[116:119]
	v_mfma_f32_16x16x32_bf16 v[84:87], v[172:175], v[210:213], v[84:87]
	v_mfma_f32_16x16x32_bf16 v[52:55], v[172:175], v[214:217], v[52:55]
	v_mfma_f32_16x16x32_bf16 v[20:23], v[172:175], v[218:221], v[20:23]
	s_waitcnt lgkmcnt(0)
	v_mfma_f32_16x16x32_bf16 v[128:131], v[156:159], v[222:225], v[128:131]
	v_mfma_f32_16x16x32_bf16 v[96:99], v[156:159], v[226:229], v[96:99]
	v_mfma_f32_16x16x32_bf16 v[64:67], v[156:159], v[230:233], v[64:67]
	v_mfma_f32_16x16x32_bf16 v[32:35], v[156:159], v[234:237], v[32:35]
	v_mfma_f32_16x16x32_bf16 v[124:127], v[160:163], v[222:225], v[124:127]
	v_mfma_f32_16x16x32_bf16 v[92:95], v[160:163], v[226:229], v[92:95]
	v_mfma_f32_16x16x32_bf16 v[60:63], v[160:163], v[230:233], v[60:63]
	v_mfma_f32_16x16x32_bf16 v[28:31], v[160:163], v[234:237], v[28:31]
	v_mfma_f32_16x16x32_bf16 v[120:123], v[194:197], v[222:225], v[120:123]
	v_mfma_f32_16x16x32_bf16 v[88:91], v[194:197], v[226:229], v[88:91]
	v_mfma_f32_16x16x32_bf16 v[56:59], v[194:197], v[230:233], v[56:59]
	v_mfma_f32_16x16x32_bf16 v[24:27], v[194:197], v[234:237], v[24:27]
	v_mfma_f32_16x16x32_bf16 v[116:119], v[198:201], v[222:225], v[116:119]
	v_mfma_f32_16x16x32_bf16 v[84:87], v[198:201], v[226:229], v[84:87]
	v_mfma_f32_16x16x32_bf16 v[52:55], v[198:201], v[230:233], v[52:55]
	v_mfma_f32_16x16x32_bf16 v[20:23], v[198:201], v[234:237], v[20:23]
	s_setprio 0
	s_waitcnt vmcnt(0)
	s_barrier
; template <int BM, int BN, int WR, int WC, int NSWAP, bool PERM = false>
; DI void gemm_ring(const int tid_, const u16* __restrict__ Ab, int lda, const u16* __restrict__ Bt, int ldb, int brow_max, int nk,
;                   char* s0, char* s1, char* s2, f32x4 (&acc)[BM / WR / 16][BN / WC / 16]) {
;     ...
;   auto step = [&](int kt, char* cur, char* nxt) {
;     if (kt + 1 < nk) WAIT_V(LPW); else WAIT_V(0);
;     raw_barrier();
;     if (kt + 2 < nk) issue(nxt, kt + 2);
;     const unsigned aA = (unsigned)(size_t)cur + (unsigned)((wr * WM) * 64 + fo);
;     const unsigned aB = (unsigned)(size_t)cur + (unsigned)(SA + (wc * WN) * 64 + fo);
;     bf16x8 xf[MT], wf[NT];
;     xf[0] = ldsr<0>(aA);
;     if constexpr (MT > 1) xf[1] = ldsr<1024>(aA);
;     if constexpr (MT > 2) xf[2] = ldsr<2048>(aA);
;     if constexpr (MT > 3) xf[3] = ldsr<3072>(aA);
;     if constexpr (MT > 4) xf[4] = ldsr<4096>(aA);
;     if constexpr (MT > 5) xf[5] = ldsr<5120>(aA);
;     wf[0] = ldsr<0>(aB);
;     if constexpr (NT > 1) wf[1] = ldsr<1024>(aB);
;     if constexpr (NT > 2) wf[2] = ldsr<2048>(aB);
;     if constexpr (NT > 3) wf[3] = ldsr<3072>(aB);
;     if constexpr (NT > 4) wf[4] = ldsr<4096>(aB);
;     if constexpr (NT > 5) wf[5] = ldsr<5120>(aB);
;     if constexpr (NT > 6) wf[6] = ldsr<6144>(aB);
;     if constexpr (NT > 7) wf[7] = ldsr<7168>(aB);
;     constexpr int NH = NT / 2;
;     asm volatile("s_waitcnt lgkmcnt(%0)" ::"n"(NT - NH) : "memory");
; #pragma unroll
;     for (int mt = 0; mt < MT; ++mt) asm volatile("" : "+v"(xf[mt]));
; #pragma unroll
;     for (int nt = 0; nt < NH; ++nt) asm volatile("" : "+v"(wf[nt]));
; #pragma unroll
;     for (int nt = 0; nt < NH; ++nt) {
; #pragma unroll
;       for (int mt = 0; mt < MT; ++mt) {
;         if (nt < NSWAP) acc[mt][nt] = __builtin_amdgcn_mfma_f32_16x16x32_bf16(wf[nt], xf[mt], acc[mt][nt], 0, 0, 0);
;         else acc[mt][nt] = __builtin_amdgcn_mfma_f32_16x16x32_bf16(xf[mt], wf[nt], acc[mt][nt], 0, 0, 0);
;       }
;     }
;     asm volatile("s_waitcnt lgkmcnt(0)" ::: "memory");
; #pragma unroll
;     for (int nt = NH; nt < NT; ++nt) asm volatile("" : "+v"(wf[nt]));
; #pragma unroll
;     for (int nt = NH; nt < NT; ++nt) {
; #pragma unroll
;       for (int mt = 0; mt < MT; ++mt) {
;         if (nt < NSWAP) acc[mt][nt] = __builtin_amdgcn_mfma_f32_16x16x32_bf16(wf[nt], xf[mt], acc[mt][nt], 0, 0, 0);
	v_add_u32_e32 v165, s72, v204
	v_add_u32_e32 v0, s72, v164
	ds_read_b128 v[238:241], v165 offset:0
	ds_read_b128 v[242:245], v165 offset:2048
	ds_read_b128 v[246:249], v165 offset:4096
	ds_read_b128 v[172:175], v165 offset:6144
	ds_read_b128 v[156:159], v0 offset:0
	ds_read_b128 v[160:163], v0 offset:2048
	ds_read_b128 v[194:197], v0 offset:4096
	ds_read_b128 v[198:201], v0 offset:6144
	s_waitcnt lgkmcnt(4)
	s_setprio 1
	v_mfma_f32_16x16x32_bf16 v[112:115], v[238:241], v[206:209], v[112:115]
	v_mfma_f32_16x16x32_bf16 v[80:83], v[238:241], v[210:213], v[80:83]
	v_mfma_f32_16x16x32_bf16 v[48:51], v[238:241], v[214:217], v[48:51]
	v_mfma_f32_16x16x32_bf16 v[16:19], v[238:241], v[218:221], v[16:19]
	v_mfma_f32_16x16x32_bf16 v[108:111], v[242:245], v[206:209], v[108:111]
	v_mfma_f32_16x16x32_bf16 v[76:79], v[242:245], v[210:213], v[76:79]
	v_mfma_f32_16x16x32_bf16 v[44:47], v[242:245], v[214:217], v[44:47]
	v_mfma_f32_16x16x32_bf16 v[12:15], v[242:245], v[218:221], v[12:15]
	v_mfma_f32_16x16x32_bf16 v[104:107], v[246:249], v[206:209], v[104:107]
	v_mfma_f32_16x16x32_bf16 v[72:75], v[246:249], v[210:213], v[72:75]
	v_mfma_f32_16x16x32_bf16 v[40:43], v[246:249], v[214:217], v[40:43]
	v_mfma_f32_16x16x32_bf16 v[8:11], v[246:249], v[218:221], v[8:11]
	v_mfma_f32_16x16x32_bf16 v[100:103], v[172:175], v[206:209], v[100:103]
	v_mfma_f32_16x16x32_bf16 v[68:71], v[172:175], v[210:213], v[68:71]
	v_mfma_f32_16x16x32_bf16 v[36:39], v[172:175], v[214:217], v[36:39]
	v_mfma_f32_16x16x32_bf16 v[4:7], v[172:175], v[218:221], v[4:7]
	s_waitcnt lgkmcnt(0)
	v_mfma_f32_16x16x32_bf16 v[112:115], v[156:159], v[222:225], v[112:115]
	v_mfma_f32_16x16x32_bf16 v[80:83], v[156:159], v[226:229], v[80:83]
	v_mfma_f32_16x16x32_bf16 v[48:51], v[156:159], v[230:233], v[48:51]
	v_mfma_f32_16x16x32_bf16 v[16:19], v[156:159], v[234:237], v[16:19]
	v_mfma_f32_16x16x32_bf16 v[108:111], v[160:163], v[222:225], v[108:111]
	v_mfma_f32_16x16x32_bf16 v[76:79], v[160:163], v[226:229], v[76:79]
	v_mfma_f32_16x16x32_bf16 v[44:47], v[160:163], v[230:233], v[44:47]
	v_mfma_f32_16x16x32_bf16 v[12:15], v[160:163], v[234:237], v[12:15]
	v_mfma_f32_16x16x32_bf16 v[104:107], v[194:197], v[222:225], v[104:107]
	v_mfma_f32_16x16x32_bf16 v[72:75], v[194:197], v[226:229], v[72:75]
	v_mfma_f32_16x16x32_bf16 v[40:43], v[194:197], v[230:233], v[40:43]
	v_mfma_f32_16x16x32_bf16 v[8:11], v[194:197], v[234:237], v[8:11]
	v_mfma_f32_16x16x32_bf16 v[100:103], v[198:201], v[222:225], v[100:103]
	v_mfma_f32_16x16x32_bf16 v[68:71], v[198:201], v[226:229], v[68:71]
	v_mfma_f32_16x16x32_bf16 v[36:39], v[198:201], v[230:233], v[36:39]
	v_mfma_f32_16x16x32_bf16 v[4:7], v[198:201], v[234:237], v[4:7]
	s_setprio 0
	s_mov_b64 s[70:71], 0x27f3a480
	s_mov_b64 s[72:73], 0x27f5a480
	s_mov_b64 s[74:75], 0x27f3a4c0
	s_mov_b64 s[76:77], 0x27f5a4c0
	s_nop 7
	s_nop 7
